# GQA dense loop also stages K/V via LDS-DMA issued after the S-phase MFMAs (as MLA in previous version)
# speedup vs baseline: 1.0410x; 1.0107x over previous
; template <int DQK, bool BAND, int QT> ...
;     ...
;   const int tid = tid_(), lane = tid & 63, w = tid >> 6, h = lane >> 5, ql = lane & 31;
;   float* bias_l = (float*)(lds + 2 * ST);
;   if (BAND) { if (tid < 129) bias_l[tid] = bias_g[tid]; }
;   bf16x8 qf[QT][NKS];
; #pragma unroll
;   for (int qt = 0; qt < QT; ++qt)
; #pragma unroll
;     for (int ks = 0; ks < NKS; ++ks) qf[qt][ks] = *(const bf16x8*)(Q + (size_t)(w * WQ + qt * 32 + ql) * DQK + ks * 16 + h * 8);
;   f32x16 o[2][QT];
; #pragma unroll
;   for (int a = 0; a < 2; ++a)
; #pragma unroll
;     for (int b = 0; b < QT; ++b)
; #pragma unroll
;       for (int r = 0; r < 16; ++r) o[a][b][r] = 0.f;
;   float m[QT], l[QT];
; #pragma unroll
;   for (int qt = 0; qt < QT; ++qt) { m[qt] = -1e30f; l[qt] = 0.f; }
;   u32x4 rk[NKL], rv[2];
;   const int vrow0 = tid >> 3, vch = tid & 7;
;   unsigned klds[NKL];
; #pragma unroll
;   for (int i = 0; i < NKL; ++i) { const int idx = tid + i * 256, kr = idx / KV4, kc = idx - kr * KV4; klds[i] = kr * KROW + kc * 16; }
;   const unsigned koff0 = (unsigned)tid * 16u;
;   const unsigned voff0 = (unsigned)(vrow0 * ldv + vch * 8) * 2u, vstep = (unsigned)(32 * ldv) * 2u;
;   const unsigned vlds0 = KST + vrow0 * LROW + vch * 16;
;   auto gload = [&](int kt) {
;     const char* kb = (const char*)Kp + (size_t)kt * (DQK * 2);
;     const char* vb = (const char*)Vt + (size_t)kt * 2;
; #pragma unroll
;     for (int i = 0; i < NKL; ++i) rk[i] = *(const u32x4*)(kb + (koff0 + i * 4096u));
; DI void phase_attn(const Ctx& c) {
;     ...
;     } else if (item < n_mla + n_gqa) {
;       const int i2 = item - n_mla;
;       const int hq = i2 & 7, rest = i2 >> 3, seq = rest / nqb, qb = rest - seq * nqb;
;       const size_t hs = (size_t)(seq * 8 + hq) * S, ks = (size_t)(seq * 2 + (hq >> 2)) * S;
;       if (ATT_PIPE) attn_dense<64>(wsb(c, OFF_QC) + (hs + qb * QBLK) * 64, wsb(c, OFF_KC) + ks * 64, wsb(c, OFF_VTC) + (size_t)(seq * 2 + (hq >> 2)) * 64 * (S + 64), S + 64,
;                      S, 0.125f * LOG2E, wsb(c, OFF_OC) + ((size_t)seq * S + qb * QBLK) * LDO + hq * 64, LDO, c.lds);
;       else attn_item<64, false, AQT>(wsb(c, OFF_QC) + (hs + qb * QBLK) * 64, wsb(c, OFF_KC) + ks * 64, wsb(c, OFF_VTC) + (size_t)(seq * 2 + (hq >> 2)) * 64 * (S + 64), S + 64,
;                      0, S, 0, nullptr, 0.125f * LOG2E, wsb(c, OFF_OC) + ((size_t)seq * S + qb * QBLK) * LDO + hq * 64, LDO, nullptr, 0, c.lds);
.LBB0_826:
	s_and_b64 vcc, exec, s[0:1]
	s_cbranch_vccz .LBB0_838
	v_readlane_b32 s0, v249, 58
	s_sub_i32 s0, s26, s0
	s_ashr_i32 s1, s0, 3
	s_ashr_i32 s7, s0, 31
	s_abs_i32 s0, s1
	v_readlane_b32 s2, v248, 3
	s_mul_hi_u32 s2, s0, s2
	v_readlane_b32 s5, v248, 2
	s_mul_i32 s3, s2, s5
	s_sub_i32 s0, s0, s3
	s_add_i32 s3, s2, 1
	s_sub_i32 s4, s0, s5
	s_cmp_ge_u32 s0, s5
	s_cselect_b32 s2, s3, s2
	s_cselect_b32 s0, s4, s0
	s_add_i32 s3, s2, 1
	s_cmp_ge_u32 s0, s5
	s_cselect_b32 s0, s3, s2
	s_xor_b32 s40, s0, s7
	s_sub_i32 s0, s40, s7
	s_lshl_b32 s2, s0, s60
	s_sub_i32 s1, s1, s2
	s_lshl_b32 s2, s0, 3
	v_readlane_b32 s3, v249, 31
	s_or_b32 s2, s2, s3
	s_lshl_b32 s4, s0, 1
	v_readlane_b32 s41, v250, 44
	s_ashr_i32 s3, s2, 31
	s_or_b32 s26, s4, s41
	s_lshl_b32 s4, s1, 8
	s_lshl_b64 s[2:3], s[2:3], s20
	s_ashr_i32 s27, s26, 31
	s_ashr_i32 s5, s4, 31
	s_add_u32 s2, s2, s4
	s_addc_u32 s3, s3, s5
	s_lshl_b64 s[2:3], s[2:3], 7
	v_readlane_b32 s1, v250, 53
	s_add_u32 s34, s1, s2
	v_readlane_b32 s1, v250, 54
	s_addc_u32 s35, s1, s3
	v_readlane_b32 s1, v248, 1
	s_lshl_b64 s[2:3], s[26:27], s1
	v_readlane_b32 s1, v250, 55
	s_add_u32 s38, s1, s2
	v_readlane_b32 s1, v250, 56
	v_mov_b32_e32 v5, v199
	s_addc_u32 s39, s1, s3
	v_readlane_b32 s1, v249, 61
	v_readlane_b32 s6, v249, 63
	v_lshlrev_b32_e32 v2, 4, v5
	v_ashrrev_i32_e32 v18, 3, v5
	s_mul_hi_i32 s27, s26, s1
	s_mul_i32 s26, s26, s1
	v_and_b32_e32 v4, 0x70, v2
	v_mul_lo_u32 v0, v18, s6
	v_bfe_u32 v196, v5, 5, 1
	v_and_b32_e32 v180, 0xffffffdf, v5
	s_lshl_b64 s[26:27], s[26:27], 1
	v_readlane_b32 s42, v250, 28
	v_or_b32_e32 v6, v4, v0
	s_waitcnt vmcnt(16)
	v_or_b32_e32 v178, 32, v5
	v_lshlrev_b32_e32 v0, 4, v196
	v_ashrrev_i32_e32 v181, 31, v180
	v_readlane_b32 s43, v250, 29
	s_add_u32 s26, s42, s26
	v_ashrrev_i32_e32 v179, 31, v178
	v_lshlrev_b64 v[12:13], 7, v[180:181]
	v_lshl_add_u64 v[16:17], s[34:35], 0, v[0:1]
	s_addc_u32 s27, s43, s27
	v_lshlrev_b64 v[14:15], 7, v[178:179]
	v_lshl_add_u64 v[12:13], v[16:17], 0, v[12:13]
	v_add_u32_e32 v8, 0x1000, v2
	global_load_dwordx4 v[130:133], v2, s[38:39]
	global_load_dwordx4 v[134:137], v8, s[38:39]
	v_add_u32_e32 v10, s1, v6
	global_load_dwordx4 v[138:141], v6, s[26:27]
	global_load_dwordx4 v[142:145], v10, s[26:27]
	v_lshl_add_u64 v[14:15], v[16:17], 0, v[14:15]
	global_load_dwordx4 v[146:149], v[12:13], off
	global_load_dwordx4 v[150:153], v[12:13], off offset:32
	global_load_dwordx4 v[154:157], v[12:13], off offset:64
	global_load_dwordx4 v[158:161], v[12:13], off offset:96
	global_load_dwordx4 v[162:165], v[14:15], off
	global_load_dwordx4 v[166:169], v[14:15], off offset:32
	global_load_dwordx4 v[170:173], v[14:15], off offset:64
	global_load_dwordx4 v[174:177], v[14:15], off offset:96
	v_ashrrev_i32_e32 v19, 31, v5
	v_add_u32_e32 v20, 0x100, v5
	v_lshrrev_b32_e32 v13, 29, v19
	v_ashrrev_i32_e32 v14, 31, v20
	v_add_u32_e32 v13, v5, v13
	v_lshrrev_b32_e32 v14, 29, v14
	v_mad_u64_u32 v[182:183], s[26:27], v18, s16, v[4:5]
	v_ashrrev_i32_e32 v13, 3, v13
	v_add_u32_e32 v4, v20, v14
	v_lshlrev_b32_e32 v16, 7, v13
	v_ashrrev_i32_e32 v17, 3, v4
	v_lshlrev_b32_e32 v15, 4, v20
	v_sub_u32_e32 v4, v2, v16
	v_lshlrev_b32_e32 v16, 7, v17
	v_mad_u64_u32 v[184:185], s[26:27], v13, s16, v[4:5]
	v_sub_u32_e32 v4, v15, v16
	v_mad_u64_u32 v[186:187], s[26:27], v17, s16, v[4:5]
	s_lshl_b32 s26, s40, 1
	s_or_b32 s26, s41, s26
	s_lshl_b32 s7, s7, 1
	s_sub_i32 s7, s26, s7
	v_readlane_b32 s26, v248, 4
	v_and_b32_e32 v12, 31, v5
	v_add_u32_e32 v4, 0, v184
	s_mul_hi_i32 s27, s26, s7
	s_mul_i32 s7, s26, s7
	v_add_u32_e32 v14, 0, v182
	v_add_u32_e32 v13, 0, v186
	v_mul_u32_u24_e32 v183, 0x90, v12
	v_lshlrev_b32_e32 v12, 1, v5
	s_add_u32 s26, s7, 0x179d5980
	s_waitcnt vmcnt(11)
	ds_write_b128 v4, v[130:133]
	s_waitcnt vmcnt(10)
	ds_write_b128 v13, v[134:137]
	s_waitcnt vmcnt(9)
	ds_write_b128 v14, v[138:141] offset:9216
	s_waitcnt vmcnt(8)
	ds_write_b128 v14, v[142:145] offset:13824
	v_and_b32_e32 v4, 19, v5
	v_lshrrev_b32_e32 v5, 1, v5
	v_and_b32_e32 v12, 8, v12
	v_and_b32_e32 v5, 4, v5
	s_addc_u32 s27, s27, 0
	v_or3_b32 v4, v4, v12, v5
	v_cmp_lt_i32_e32 vcc, v221, v220
	s_add_u32 s2, s2, 0x175d7900
	v_mov_b32_e32 v3, v1
	v_mov_b32_e32 v9, v1
	v_mov_b32_e32 v7, v1
	v_mov_b32_e32 v11, v1
	v_mul_u32_u24_e32 v185, 0x90, v4
	v_cndmask_b32_e32 v4, v219, v221, vcc
	s_addc_u32 s3, s3, 0
	v_mov_b32_e32 v50, v1
	v_mov_b32_e32 v51, v1
	v_lshlrev_b32_e32 v179, 2, v4
	v_lshl_add_u64 v[188:189], s[26:27], 0, v[6:7]
	v_lshl_add_u64 v[190:191], s[26:27], 0, v[10:11]
	v_lshl_add_u64 v[192:193], s[2:3], 0, v[2:3]
	v_lshl_add_u64 v[194:195], s[2:3], 0, v[8:9]
	v_mov_b32_e32 v52, v1
	v_mov_b32_e32 v53, v1
	v_mov_b32_e32 v54, v1
	v_mov_b32_e32 v55, v1
	v_mov_b32_e32 v56, v1
	v_mov_b32_e32 v57, v1
	v_mov_b32_e32 v58, v1
	v_mov_b32_e32 v59, v1
	v_mov_b32_e32 v60, v1
	v_mov_b32_e32 v61, v1
	v_mov_b32_e32 v62, v1
	v_mov_b32_e32 v63, v1
	v_mov_b32_e32 v64, v1
	v_mov_b32_e32 v65, v1
	v_mov_b64_e32 v[18:19], v[50:51]
	v_mov_b64_e32 v[34:35], v[50:51]
	v_mov_b64_e32 v[2:3], v[50:51]
	s_mov_b32 s1, 0
	s_mov_b32 s6, 64
	v_mov_b32_e32 v197, 0xf149f2ca
	v_mov_b32_e32 v187, 0
	v_mov_b32_e32 v181, 0
	v_mov_b32_e32 v202, 0xf149f2ca
	v_mov_b64_e32 v[20:21], v[52:53]
	v_mov_b64_e32 v[22:23], v[54:55]
	v_mov_b64_e32 v[24:25], v[56:57]
	v_mov_b64_e32 v[26:27], v[58:59]
	v_mov_b64_e32 v[28:29], v[60:61]
	v_mov_b64_e32 v[30:31], v[62:63]
	v_mov_b64_e32 v[32:33], v[64:65]
	v_mov_b64_e32 v[36:37], v[52:53]
	v_mov_b64_e32 v[38:39], v[54:55]
	v_mov_b64_e32 v[40:41], v[56:57]
	v_mov_b64_e32 v[42:43], v[58:59]
	v_mov_b64_e32 v[44:45], v[60:61]
	v_mov_b64_e32 v[46:47], v[62:63]
	v_mov_b64_e32 v[48:49], v[64:65]
; template <int DQK, bool BAND, int QT> ...
;     ...
;   u32x4 rk[NKL], rv[2];
;   const int vrow0 = tid >> 3, vch = tid & 7;
;   unsigned klds[NKL];
; #pragma unroll
;   for (int i = 0; i < NKL; ++i) { const int idx = tid + i * 256, kr = idx / KV4, kc = idx - kr * KV4; klds[i] = kr * KROW + kc * 16; }
;   const unsigned koff0 = (unsigned)tid * 16u;
;   const unsigned voff0 = (unsigned)(vrow0 * ldv + vch * 8) * 2u, vstep = (unsigned)(32 * ldv) * 2u;
;   const unsigned vlds0 = KST + vrow0 * LROW + vch * 16;
;   auto gload = [&](int kt) {
;     const char* kb = (const char*)Kp + (size_t)kt * (DQK * 2);
;     const char* vb = (const char*)Vt + (size_t)kt * 2;
; #pragma unroll
;     for (int i = 0; i < NKL; ++i) rk[i] = *(const u32x4*)(kb + (koff0 + i * 4096u));
; #pragma unroll
;     for (int i = 0; i < 2; ++i) rv[i] = *(const u32x4*)(vb + (voff0 + i * vstep));
;   };
;   auto lstore = [&](char* st) {
; #pragma unroll
;     for (int i = 0; i < NKL; ++i) *(u32x4*)(st + klds[i]) = rk[i];
; #pragma unroll
;     for (int i = 0; i < 2; ++i) *(u32x4*)(st + vlds0 + i * 32 * LROW) = rv[i];
;   };
;   gload(kbeg);
;   lstore(lds);
;   __syncthreads();
;   const int pr = (ql & ~12) | ((ql & 4) << 1) | ((ql & 8) >> 1);
;   const int k_rd = pr * KROW + h * 16;
;   const int v_rd = KST + ql * LROW + h * 16;
;   const int qw0 = q0 + w * WQ;
	v_mov_b64_e32 v[4:5], v[52:53]
	v_mov_b64_e32 v[6:7], v[54:55]
	v_mov_b64_e32 v[8:9], v[56:57]
	v_mov_b64_e32 v[10:11], v[58:59]
	v_mov_b64_e32 v[12:13], v[60:61]
	v_mov_b64_e32 v[14:15], v[62:63]
	v_mov_b64_e32 v[16:17], v[64:65]
	v_add_u32_e32 v185, v185, v0
	v_add_u32_e32 v183, v183, v0
	v_mbcnt_lo_u32_b32 v254, -1, 0
	v_mbcnt_hi_u32_b32 v254, -1, v254
	v_and_b32_e32 v255, 15, v254
	v_lshrrev_b32_e32 v253, 4, v254
	v_and_b32_e32 v253, 1, v253
	v_cmp_eq_u32_e32 vcc, v255, v253
	v_mov_b32_e32 v253, 0x3f803f80
	s_nop 1
	v_cndmask_b32_e32 v244, 0, v253, vcc
	v_mov_b32_e32 v245, v244
	v_mov_b32_e32 v246, v244
	v_mov_b32_e32 v247, v244
	v_mov_b32_e32 v236, 0
	v_mov_b32_e32 v237, 0
	v_mov_b32_e32 v238, 0
	v_mov_b32_e32 v239, 0
	v_mov_b32_e32 v240, 0
	v_mov_b32_e32 v241, 0
	v_mov_b32_e32 v242, 0
	v_mov_b32_e32 v243, 0
	v_readfirstlane_b32 s38, v199
	s_lshr_b32 s38, s38, 6
	s_lshl_b32 s39, s38, 10
	v_readlane_b32 s25, v249, 63
	v_mov_b32_e32 v253, v199
	v_mul_u32_u24_e32 v254, 0x1c72, v253
	v_lshrrev_b32_e32 v254, 16, v254
	v_mul_u32_u24_e32 v255, 9, v254
	v_sub_u32_e32 v255, v253, v255
	v_min_u32_e32 v255, 7, v255
	v_mul_u32_u24_e32 v254, 0x80, v254
	v_lshl_add_u32 v130, v255, 4, v254
	v_add_u32_e32 v253, 0x100, v199
	v_mul_u32_u24_e32 v254, 0x1c72, v253
	v_lshrrev_b32_e32 v254, 16, v254
	v_mul_u32_u24_e32 v255, 9, v254
	v_sub_u32_e32 v255, v253, v255
	v_min_u32_e32 v255, 7, v255
	v_mul_u32_u24_e32 v254, 0x80, v254
	v_lshl_add_u32 v131, v255, 4, v254
	v_mov_b32_e32 v253, v199
	v_mul_u32_u24_e32 v254, 0x1c72, v253
	v_lshrrev_b32_e32 v254, 16, v254
	v_mul_u32_u24_e32 v255, 9, v254
	v_sub_u32_e32 v255, v253, v255
	v_min_u32_e32 v255, 7, v255
	v_mul_lo_u32 v254, v254, s25
	v_lshl_add_u32 v132, v255, 4, v254
	v_add_u32_e32 v253, 0x100, v199
	v_mul_u32_u24_e32 v254, 0x1c72, v253
	v_lshrrev_b32_e32 v254, 16, v254
	v_mul_u32_u24_e32 v255, 9, v254
	v_sub_u32_e32 v255, v253, v255
	v_min_u32_e32 v255, 7, v255
	v_mul_lo_u32 v254, v254, s25
	v_lshl_add_u32 v133, v255, 4, v254
	v_add_u32_e32 v253, 0x200, v199
	v_mul_u32_u24_e32 v254, 0x1c72, v253
	v_lshrrev_b32_e32 v254, 16, v254
	v_mul_u32_u24_e32 v255, 9, v254
	v_sub_u32_e32 v255, v253, v255
	v_min_u32_e32 v255, 7, v255
	v_mul_u32_u24_e32 v254, 0x80, v254
	v_lshl_add_u32 v134, v255, 4, v254
	v_add_u32_e32 v253, 0x1c0, v199
	v_mul_u32_u24_e32 v254, 0x1c72, v253
	v_lshrrev_b32_e32 v254, 16, v254
	v_mul_u32_u24_e32 v255, 9, v254
	v_sub_u32_e32 v255, v253, v255
	v_min_u32_e32 v255, 7, v255
	v_mul_lo_u32 v254, v254, s25
	v_lshl_add_u32 v135, v255, 4, v254
	v_cmp_gt_u32_e32 vcc, 64, v199
	s_nop 1
	v_cndmask_b32_e32 v134, v135, v134, vcc
	v_readfirstlane_b32 s34, v192
	v_readfirstlane_b32 s35, v193
	s_add_u32 s34, s34, s94
	s_addc_u32 s35, s35, s95
	s_sub_u32 s34, s34, s39
	s_subb_u32 s35, s35, 0
	v_readfirstlane_b32 s26, v188
	v_readfirstlane_b32 s27, v189
	s_add_u32 s26, s26, s94
	s_addc_u32 s27, s27, s95
	s_mul_i32 s42, s38, s25
	s_lshl_b32 s42, s42, 3
	s_sub_u32 s26, s26, s42
	s_subb_u32 s27, s27, 0
	s_waitcnt vmcnt(0) lgkmcnt(0)
	s_barrier
; #define MFMA(a, b, c) __builtin_amdgcn_mfma_f32_32x32x16_bf16((a), (b), (c), 0, 0, 0)
; template <int DQK, bool BAND, int QT> ...
;     ...
;   for (int kt = kbeg; kt < kend; kt += 64, ++it) {
;     const char* st = lds + (it & 1) * ST;
;     const bool more = (kt + 64 < kend);
;     if (more) gload(kt + 64);
;     bool need = true;
;     if (BAND) need = (kt + 63 >= qw0 - 64) && (kt <= qw0 + WQ - 1 + 64);
;     if (need) {
;       f32x16 s[2][QT];
; #pragma unroll
;       for (int a = 0; a < 2; ++a)
; #pragma unroll
;         for (int b = 0; b < QT; ++b)
; #pragma unroll
;           for (int r = 0; r < 16; ++r) s[a][b][r] = 0.f;
; #pragma unroll
;       for (int ks = 0; ks < NKS; ++ks) {
;         const bf16x8 k0 = *(const bf16x8*)(st + k_rd + ks * 32);
;         const bf16x8 k1 = *(const bf16x8*)(st + k_rd + 32 * KROW + ks * 32);
; #pragma unroll
;         for (int qt = 0; qt < QT; ++qt) {
;           s[0][qt] = MFMA(k0, qf[qt][ks], s[0][qt]);
;           s[1][qt] = MFMA(k1, qf[qt][ks], s[1][qt]);
;         }
;       }
;       __builtin_amdgcn_s_setprio(3);
;       bf16x8 pf[QT][4];
;       const float cc = BAND ? 1.0f : scale_log2;
;       const float th = BAND ? 8.0f : 8.0f / scale_log2;
; #pragma unroll
;       for (int qt = 0; qt < QT; ++qt) {
;         if (BAND) {
; #pragma unroll
;           for (int a = 0; a < 2; ++a)
; #pragma unroll
;             for (int r = 0; r < 16; ++r) {
;               const int kidx = kt + 32 * a + (r & 7) + 8 * h + 16 * (r >> 3);
;               const int rel = kidx - (qw0 + qt * 32 + ql);
;               const bool ok = (rel >= -64) && (rel <= 64);
;               const int bi = ok ? rel + 64 : 0;
;               s[a][qt][r] = ok ? fmaf(s[a][qt][r], scale_log2, bias_l[bi]) : -1e30f;
;             }
;         }
;         float mx = s[0][qt][0];
; #pragma unroll
;         for (int r = 1; r < 16; ++r) mx = fmaxf(mx, s[0][qt][r]);
; #pragma unroll
;         for (int r = 0; r < 16; ++r) mx = fmaxf(mx, s[1][qt][r]);
;         mx = fmaxf(mx, __shfl_xor(mx, 32));
;         if (__builtin_amdgcn_ballot_w64(mx > m[qt] + th) != 0) {
;           const float mn = fmaxf(m[qt], mx);
;           const float alpha = __builtin_amdgcn_exp2f((m[qt] - mn) * cc);
;           m[qt] = mn;
;           l[qt] *= alpha;
; #pragma unroll
;           for (int r = 0; r < 16; ++r) { o[0][qt][r] *= alpha; o[1][qt][r] *= alpha; }
;         }
.Lgqa_top:
	ds_read_b128 v[206:209], v185
	ds_read_b128 v[210:213], v185 offset:4608
	ds_read_b128 v[214:217], v185 offset:32
	ds_read_b128 v[232:235], v185 offset:4640
	s_waitcnt lgkmcnt(3)
	v_mfma_f32_32x32x16_bf16 v[82:97], v[206:209], v[146:149], 0
	v_mfma_f32_32x32x16_bf16 v[114:129], v[206:209], v[162:165], 0
	ds_read_b128 v[206:209], v185 offset:64
	s_waitcnt lgkmcnt(3)
	v_mfma_f32_32x32x16_bf16 v[66:81], v[210:213], v[146:149], 0
	v_mfma_f32_32x32x16_bf16 v[98:113], v[210:213], v[162:165], 0
	ds_read_b128 v[210:213], v185 offset:4672
	s_waitcnt lgkmcnt(3)
	v_mfma_f32_32x32x16_bf16 v[82:97], v[214:217], v[150:153], v[82:97]
	v_mfma_f32_32x32x16_bf16 v[114:129], v[214:217], v[166:169], v[114:129]
	ds_read_b128 v[214:217], v185 offset:96
	s_waitcnt lgkmcnt(3)
	v_mfma_f32_32x32x16_bf16 v[66:81], v[232:235], v[150:153], v[66:81]
	v_mfma_f32_32x32x16_bf16 v[98:113], v[232:235], v[166:169], v[98:113]
	ds_read_b128 v[232:235], v185 offset:4704
	s_waitcnt lgkmcnt(3)
	v_mfma_f32_32x32x16_bf16 v[82:97], v[206:209], v[154:157], v[82:97]
	v_mfma_f32_32x32x16_bf16 v[114:129], v[206:209], v[170:173], v[114:129]
	s_waitcnt lgkmcnt(2)
	v_mfma_f32_32x32x16_bf16 v[66:81], v[210:213], v[154:157], v[66:81]
	v_mfma_f32_32x32x16_bf16 v[98:113], v[210:213], v[170:173], v[98:113]
	s_waitcnt lgkmcnt(1)
	v_mfma_f32_32x32x16_bf16 v[82:97], v[214:217], v[158:161], v[82:97]
	v_mfma_f32_32x32x16_bf16 v[114:129], v[214:217], v[174:177], v[114:129]
	s_waitcnt lgkmcnt(0)
	v_mfma_f32_32x32x16_bf16 v[66:81], v[232:235], v[158:161], v[66:81]
	v_mfma_f32_32x32x16_bf16 v[98:113], v[232:235], v[174:177], v[98:113]
	s_cmp_lt_u32 s6, s19
	s_cbranch_scc0 .Lgqa_dma_noload
	s_andn2_b32 s2, 1, s1
	s_mulk_i32 s2, 0x4800
	s_add_u32 s2, s2, s39
	s_mov_b32 m0, s2
	s_add_u32 s3, s2, 0x1000
	global_load_lds_dwordx4 v130, s[34:35]
	s_mov_b32 m0, s3
	s_add_u32 s3, s2, 0x2400
	global_load_lds_dwordx4 v131, s[34:35]
	s_mov_b32 m0, s3
	s_add_u32 s3, s2, 0x3400
	global_load_lds_dwordx4 v132, s[26:27]
	s_mov_b32 m0, s3
	s_sub_u32 s3, s2, s39
	global_load_lds_dwordx4 v133, s[26:27]
	s_cmp_gt_u32 s38, 1
	s_cbranch_scc1 .Lgqa_dma_x2
	s_cmp_eq_u32 s38, 0
	s_cbranch_scc0 .Lgqa_dma_x1
	s_add_u32 m0, s3, 0x2000
	s_nop 0
	global_load_lds_dwordx4 v134, s[34:35]
	s_branch .Lgqa_dma_x2
.Lgqa_dma_x1:
	s_add_u32 m0, s3, 0x4400
	s_nop 0
	global_load_lds_dwordx4 v134, s[26:27]
.Lgqa_dma_x2:
	s_add_u32 s34, s34, s88
	s_addc_u32 s35, s35, s89
	s_add_u32 s26, s26, s76
	s_addc_u32 s27, s27, s77
.Lgqa_dma_noload:
	s_nop 7
	s_setprio 0
	v_max_f32_e32 v203, v82, v83
	v_max_f32_e32 v253, v114, v115
	v_max3_f32 v203, v203, v84, v85
	v_max3_f32 v253, v253, v116, v117
	v_max3_f32 v203, v203, v86, v87
	v_max3_f32 v253, v253, v118, v119
	v_max3_f32 v203, v203, v88, v89
	v_max3_f32 v253, v253, v120, v121
	v_max3_f32 v203, v203, v90, v91
	v_max3_f32 v253, v253, v122, v123
	v_max3_f32 v203, v203, v92, v93
	v_max3_f32 v253, v253, v124, v125
	v_max3_f32 v203, v203, v94, v95
	v_max3_f32 v253, v253, v126, v127
	v_max3_f32 v203, v203, v96, v97
	v_max3_f32 v253, v253, v128, v129
	v_max3_f32 v203, v203, v66, v67
	v_max3_f32 v253, v253, v98, v99
	v_max3_f32 v203, v203, v68, v69
	v_max3_f32 v253, v253, v100, v101
	v_max3_f32 v203, v203, v70, v71
	v_max3_f32 v253, v253, v102, v103
	v_max3_f32 v203, v203, v72, v73
	v_max3_f32 v253, v253, v104, v105
	v_max3_f32 v203, v203, v74, v75
	v_max3_f32 v253, v253, v106, v107
	v_max3_f32 v203, v203, v76, v77
	v_max3_f32 v253, v253, v108, v109
	v_max3_f32 v203, v203, v78, v79
	v_max3_f32 v253, v253, v110, v111
	v_max3_f32 v203, v203, v80, v81
	v_max3_f32 v253, v253, v112, v113
	v_add_f32_e32 v254, 0x42317218, v197
	v_cmp_gt_f32_e32 vcc, v203, v254
	s_cbranch_vccz .Lgqa_nr0
	ds_bpermute_b32 v254, v179, v203
	s_waitcnt lgkmcnt(0)
	v_max_f32_e32 v254, v254, v254
	v_max_f32_e32 v203, v203, v254
	v_max_f32_e32 v254, v197, v197
	v_max_f32_e32 v203, v254, v203
	v_sub_f32_e32 v197, v197, v203
	v_mul_f32_e32 v197, 0x3e38aa3b, v197
	v_exp_f32_e32 v254, v197
	v_mov_b32_e32 v197, v203
	v_pk_mul_f32 v[64:65], v[64:65], v[254:255] op_sel_hi:[1,0]
	v_pk_mul_f32 v[62:63], v[62:63], v[254:255] op_sel_hi:[1,0]
	v_pk_mul_f32 v[60:61], v[60:61], v[254:255] op_sel_hi:[1,0]
	v_pk_mul_f32 v[58:59], v[58:59], v[254:255] op_sel_hi:[1,0]
	v_pk_mul_f32 v[56:57], v[56:57], v[254:255] op_sel_hi:[1,0]
	v_pk_mul_f32 v[54:55], v[54:55], v[254:255] op_sel_hi:[1,0]
	v_pk_mul_f32 v[52:53], v[52:53], v[254:255] op_sel_hi:[1,0]
	v_pk_mul_f32 v[50:51], v[50:51], v[254:255] op_sel_hi:[1,0]
	v_pk_mul_f32 v[48:49], v[48:49], v[254:255] op_sel_hi:[1,0]
	v_pk_mul_f32 v[46:47], v[46:47], v[254:255] op_sel_hi:[1,0]
	v_pk_mul_f32 v[44:45], v[44:45], v[254:255] op_sel_hi:[1,0]
	v_pk_mul_f32 v[42:43], v[42:43], v[254:255] op_sel_hi:[1,0]
	v_pk_mul_f32 v[40:41], v[40:41], v[254:255] op_sel_hi:[1,0]
	v_pk_mul_f32 v[38:39], v[38:39], v[254:255] op_sel_hi:[1,0]
	v_pk_mul_f32 v[36:37], v[36:37], v[254:255] op_sel_hi:[1,0]
	v_pk_mul_f32 v[34:35], v[34:35], v[254:255] op_sel_hi:[1,0]
	v_mbcnt_lo_u32_b32 v255, -1, 0
	v_mbcnt_hi_u32_b32 v255, -1, v255
	v_add_u32_e32 v255, 16, v255
	v_lshlrev_b32_e32 v255, 2, v255
	ds_bpermute_b32 v255, v255, v254
	s_waitcnt lgkmcnt(0)
	v_mul_f32_e32 v240, v240, v254
	v_mul_f32_e32 v241, v241, v255

; DI unsigned pk2(float a, float b) { f32x2 v = {a, b}; bf16x2_t r = __builtin_convertvector(v, bf16x2_t); return __builtin_bit_cast(unsigned, r); }
; template <int DQK, bool BAND, int QT> ...
;     ...
;         const float mc = -m[qt] * cc;
;         float ls = 0.f;
; #pragma unroll
;         for (int a = 0; a < 2; ++a) {
; #pragma unroll
;           for (int r = 0; r < 16; ++r) { const float pv = __builtin_amdgcn_exp2f(fmaf(s[a][qt][r], cc, mc)); s[a][qt][r] = pv; ls += pv; }
; #pragma unroll
;           for (int s2 = 0; s2 < 2; ++s2) {
;             u32x4 pk;
;             pk.x = pk2(s[a][qt][8 * s2 + 0], s[a][qt][8 * s2 + 1]);
;             pk.y = pk2(s[a][qt][8 * s2 + 2], s[a][qt][8 * s2 + 3]);
;             pk.z = pk2(s[a][qt][8 * s2 + 4], s[a][qt][8 * s2 + 5]);
;             pk.w = pk2(s[a][qt][8 * s2 + 6], s[a][qt][8 * s2 + 7]);
;             pf[qt][a * 2 + s2] = __builtin_bit_cast(bf16x8, pk);
;           }
;         }
;         l[qt] += ls;
;       }
;       __builtin_amdgcn_s_setprio(0);
;       if (more) lstore(lds + ((it + 1) & 1) * ST);
; #pragma unroll
;       for (int ks = 0; ks < 4; ++ks) {
;         const bf16x8 v0 = *(const bf16x8*)(st + v_rd + ks * 32);
.Lgqa_nr1:
	v_mul_f32_e32 v254, 0xbe38aa3b, v197
	v_mul_f32_e32 v255, 0xbe38aa3b, v202
	v_fmamk_f32 v82, v82, 0x3e38aa3b, v254
	v_fmamk_f32 v114, v114, 0x3e38aa3b, v255
	v_fmamk_f32 v83, v83, 0x3e38aa3b, v254
	v_fmamk_f32 v115, v115, 0x3e38aa3b, v255
	v_fmamk_f32 v84, v84, 0x3e38aa3b, v254
	v_fmamk_f32 v116, v116, 0x3e38aa3b, v255
	v_fmamk_f32 v85, v85, 0x3e38aa3b, v254
	v_fmamk_f32 v117, v117, 0x3e38aa3b, v255
	v_fmamk_f32 v86, v86, 0x3e38aa3b, v254
	v_fmamk_f32 v118, v118, 0x3e38aa3b, v255
	v_fmamk_f32 v87, v87, 0x3e38aa3b, v254
	v_fmamk_f32 v119, v119, 0x3e38aa3b, v255
	v_fmamk_f32 v88, v88, 0x3e38aa3b, v254
	v_fmamk_f32 v120, v120, 0x3e38aa3b, v255
	v_fmamk_f32 v89, v89, 0x3e38aa3b, v254
	v_fmamk_f32 v121, v121, 0x3e38aa3b, v255
	v_exp_f32_e32 v82, v82
	v_exp_f32_e32 v114, v114
	v_exp_f32_e32 v83, v83
	v_exp_f32_e32 v115, v115
	v_exp_f32_e32 v84, v84
	v_exp_f32_e32 v116, v116
	v_exp_f32_e32 v85, v85
	v_exp_f32_e32 v117, v117
	v_exp_f32_e32 v86, v86
	v_exp_f32_e32 v118, v118
	v_exp_f32_e32 v87, v87
	v_exp_f32_e32 v119, v119
	v_exp_f32_e32 v88, v88
	v_exp_f32_e32 v120, v120
	v_exp_f32_e32 v89, v89
	v_exp_f32_e32 v121, v121
	v_fmamk_f32 v90, v90, 0x3e38aa3b, v254
	v_fmamk_f32 v122, v122, 0x3e38aa3b, v255
	v_fmamk_f32 v91, v91, 0x3e38aa3b, v254
	v_fmamk_f32 v123, v123, 0x3e38aa3b, v255
	v_fmamk_f32 v92, v92, 0x3e38aa3b, v254
	v_fmamk_f32 v124, v124, 0x3e38aa3b, v255
	v_fmamk_f32 v93, v93, 0x3e38aa3b, v254
	v_fmamk_f32 v125, v125, 0x3e38aa3b, v255
	v_fmamk_f32 v94, v94, 0x3e38aa3b, v254
	v_fmamk_f32 v126, v126, 0x3e38aa3b, v255
	v_fmamk_f32 v95, v95, 0x3e38aa3b, v254
	v_fmamk_f32 v127, v127, 0x3e38aa3b, v255
	v_fmamk_f32 v96, v96, 0x3e38aa3b, v254
	v_fmamk_f32 v128, v128, 0x3e38aa3b, v255
	v_fmamk_f32 v97, v97, 0x3e38aa3b, v254
	v_fmamk_f32 v129, v129, 0x3e38aa3b, v255
	v_exp_f32_e32 v90, v90
	v_exp_f32_e32 v122, v122
	v_exp_f32_e32 v91, v91
	v_exp_f32_e32 v123, v123
	v_exp_f32_e32 v92, v92
	v_exp_f32_e32 v124, v124
	v_exp_f32_e32 v93, v93
	v_exp_f32_e32 v125, v125
	v_exp_f32_e32 v94, v94
	v_exp_f32_e32 v126, v126
	v_exp_f32_e32 v95, v95
	v_exp_f32_e32 v127, v127
	v_exp_f32_e32 v96, v96
	v_exp_f32_e32 v128, v128
	v_exp_f32_e32 v97, v97
	v_exp_f32_e32 v129, v129
	v_cvt_pk_bf16_f32 v82, v82, v83
	v_cvt_pk_bf16_f32 v114, v114, v115
	v_cvt_pk_bf16_f32 v83, v84, v85
	v_cvt_pk_bf16_f32 v115, v116, v117
	v_cvt_pk_bf16_f32 v84, v86, v87
	v_cvt_pk_bf16_f32 v116, v118, v119
	v_cvt_pk_bf16_f32 v85, v88, v89
	v_cvt_pk_bf16_f32 v117, v120, v121
	v_fmamk_f32 v66, v66, 0x3e38aa3b, v254
	v_fmamk_f32 v98, v98, 0x3e38aa3b, v255
	v_fmamk_f32 v67, v67, 0x3e38aa3b, v254
	v_fmamk_f32 v99, v99, 0x3e38aa3b, v255
	v_fmamk_f32 v68, v68, 0x3e38aa3b, v254
	v_fmamk_f32 v100, v100, 0x3e38aa3b, v255
	v_fmamk_f32 v69, v69, 0x3e38aa3b, v254
	v_fmamk_f32 v101, v101, 0x3e38aa3b, v255
	v_fmamk_f32 v70, v70, 0x3e38aa3b, v254
	v_fmamk_f32 v102, v102, 0x3e38aa3b, v255
	v_fmamk_f32 v71, v71, 0x3e38aa3b, v254
	v_fmamk_f32 v103, v103, 0x3e38aa3b, v255
	v_fmamk_f32 v72, v72, 0x3e38aa3b, v254
	v_fmamk_f32 v104, v104, 0x3e38aa3b, v255
	v_fmamk_f32 v73, v73, 0x3e38aa3b, v254
	v_fmamk_f32 v105, v105, 0x3e38aa3b, v255
	v_exp_f32_e32 v66, v66
	v_exp_f32_e32 v98, v98
	v_exp_f32_e32 v67, v67
	v_exp_f32_e32 v99, v99
	v_exp_f32_e32 v68, v68
	v_exp_f32_e32 v100, v100
	v_exp_f32_e32 v69, v69
	v_exp_f32_e32 v101, v101
	v_exp_f32_e32 v70, v70
	v_exp_f32_e32 v102, v102
	v_exp_f32_e32 v71, v71
	v_exp_f32_e32 v103, v103
	v_exp_f32_e32 v72, v72
	v_exp_f32_e32 v104, v104
	v_exp_f32_e32 v73, v73
	v_exp_f32_e32 v105, v105
	v_cvt_pk_bf16_f32 v90, v90, v91
	v_cvt_pk_bf16_f32 v122, v122, v123
	v_cvt_pk_bf16_f32 v91, v92, v93
	v_cvt_pk_bf16_f32 v123, v124, v125
	v_cvt_pk_bf16_f32 v92, v94, v95
	v_cvt_pk_bf16_f32 v124, v126, v127
	v_cvt_pk_bf16_f32 v93, v96, v97
	v_cvt_pk_bf16_f32 v125, v128, v129
	v_fmamk_f32 v74, v74, 0x3e38aa3b, v254
	v_fmamk_f32 v106, v106, 0x3e38aa3b, v255
	v_fmamk_f32 v75, v75, 0x3e38aa3b, v254
	v_fmamk_f32 v107, v107, 0x3e38aa3b, v255
	v_fmamk_f32 v76, v76, 0x3e38aa3b, v254
	v_fmamk_f32 v108, v108, 0x3e38aa3b, v255
	v_fmamk_f32 v77, v77, 0x3e38aa3b, v254
	v_fmamk_f32 v109, v109, 0x3e38aa3b, v255
	v_fmamk_f32 v78, v78, 0x3e38aa3b, v254
	v_fmamk_f32 v110, v110, 0x3e38aa3b, v255
	v_fmamk_f32 v79, v79, 0x3e38aa3b, v254
	v_fmamk_f32 v111, v111, 0x3e38aa3b, v255
	v_fmamk_f32 v80, v80, 0x3e38aa3b, v254
	v_fmamk_f32 v112, v112, 0x3e38aa3b, v255
	v_fmamk_f32 v81, v81, 0x3e38aa3b, v254
	v_fmamk_f32 v113, v113, 0x3e38aa3b, v255
	v_exp_f32_e32 v74, v74
	v_exp_f32_e32 v106, v106
	v_exp_f32_e32 v75, v75
	v_exp_f32_e32 v107, v107
	v_exp_f32_e32 v76, v76
	v_exp_f32_e32 v108, v108
	v_exp_f32_e32 v77, v77
	v_exp_f32_e32 v109, v109
	v_exp_f32_e32 v78, v78
	v_exp_f32_e32 v110, v110
	v_exp_f32_e32 v79, v79
	v_exp_f32_e32 v111, v111
	v_exp_f32_e32 v80, v80
	v_exp_f32_e32 v112, v112
	v_exp_f32_e32 v81, v81
	v_exp_f32_e32 v113, v113
	v_cvt_pk_bf16_f32 v66, v66, v67
	v_cvt_pk_bf16_f32 v98, v98, v99
	v_cvt_pk_bf16_f32 v67, v68, v69
	v_cvt_pk_bf16_f32 v99, v100, v101
	v_cvt_pk_bf16_f32 v68, v70, v71
	v_cvt_pk_bf16_f32 v100, v102, v103
	v_cvt_pk_bf16_f32 v69, v72, v73
	v_cvt_pk_bf16_f32 v101, v104, v105
	v_cvt_pk_bf16_f32 v74, v74, v75
	v_cvt_pk_bf16_f32 v106, v106, v107
	v_cvt_pk_bf16_f32 v75, v76, v77
	v_cvt_pk_bf16_f32 v107, v108, v109
	v_cvt_pk_bf16_f32 v76, v78, v79
	v_cvt_pk_bf16_f32 v108, v110, v111
	v_cvt_pk_bf16_f32 v77, v80, v81
	v_cvt_pk_bf16_f32 v109, v112, v113
	s_setprio 2
	ds_read_b128 v[86:89], v183 offset:9216
	ds_read_b128 v[94:97], v183 offset:13824
	ds_read_b128 v[70:73], v183 offset:9248
	ds_read_b128 v[78:81], v183 offset:13856
	ds_read_b128 v[118:121], v183 offset:9280
	ds_read_b128 v[126:129], v183 offset:13888
	ds_read_b128 v[102:105], v183 offset:9312
	ds_read_b128 v[110:113], v183 offset:13920
	s_waitcnt lgkmcnt(7)
; #define MFMA(a, b, c) __builtin_amdgcn_mfma_f32_32x32x16_bf16((a), (b), (c), 0, 0, 0)
; template <int DQK, bool BAND, int QT> ...
;     ...
; #pragma unroll
;       for (int ks = 0; ks < 4; ++ks) {
;         const bf16x8 v0 = *(const bf16x8*)(st + v_rd + ks * 32);
;         const bf16x8 v1 = *(const bf16x8*)(st + v_rd + 32 * LROW + ks * 32);
; #pragma unroll
;         for (int qt = 0; qt < QT; ++qt) {
;           o[0][qt] = MFMA(v0, pf[qt][ks], o[0][qt]);
;           o[1][qt] = MFMA(v1, pf[qt][ks], o[1][qt]);
;         }
;       }
;     } else {
;       if (more) lstore(lds + ((it + 1) & 1) * ST);
;     }
;     __syncthreads();
;   }
; #pragma unroll
;   for (int qt = 0; qt < QT; ++qt) {
;     const float lt = l[qt] + __shfl_xor(l[qt], 32);
;     const float inv = __builtin_amdgcn_rcpf(lt);
	v_mfma_f32_32x32x16_bf16 v[50:65], v[86:89], v[82:85], v[50:65]
	v_mfma_f32_32x32x16_bf16 v[18:33], v[86:89], v[114:117], v[18:33]
	s_waitcnt lgkmcnt(6)
	v_mfma_f32_32x32x16_bf16 v[34:49], v[94:97], v[82:85], v[34:49]
	v_mfma_f32_32x32x16_bf16 v[2:17], v[94:97], v[114:117], v[2:17]
	v_mfma_f32_16x16x32_bf16 v[240:243], v[244:247], v[82:85], v[240:243]
	v_mfma_f32_16x16x32_bf16 v[236:239], v[244:247], v[114:117], v[236:239]
	s_waitcnt lgkmcnt(5)
	v_mfma_f32_32x32x16_bf16 v[50:65], v[70:73], v[90:93], v[50:65]
	v_mfma_f32_32x32x16_bf16 v[18:33], v[70:73], v[122:125], v[18:33]
	s_waitcnt lgkmcnt(4)
	v_mfma_f32_32x32x16_bf16 v[34:49], v[78:81], v[90:93], v[34:49]
	v_mfma_f32_32x32x16_bf16 v[2:17], v[78:81], v[122:125], v[2:17]
	v_mfma_f32_16x16x32_bf16 v[240:243], v[244:247], v[90:93], v[240:243]
	v_mfma_f32_16x16x32_bf16 v[236:239], v[244:247], v[122:125], v[236:239]
	s_waitcnt lgkmcnt(3)
	v_mfma_f32_32x32x16_bf16 v[50:65], v[118:121], v[66:69], v[50:65]
	v_mfma_f32_32x32x16_bf16 v[18:33], v[118:121], v[98:101], v[18:33]
	s_waitcnt lgkmcnt(2)
	v_mfma_f32_32x32x16_bf16 v[34:49], v[126:129], v[66:69], v[34:49]
	v_mfma_f32_32x32x16_bf16 v[2:17], v[126:129], v[98:101], v[2:17]
	v_mfma_f32_16x16x32_bf16 v[240:243], v[244:247], v[66:69], v[240:243]
	v_mfma_f32_16x16x32_bf16 v[236:239], v[244:247], v[98:101], v[236:239]
	s_bitcmp1_b32 s1, 0
	s_cselect_b32 s7, -1, 1
	s_mulk_i32 s7, 0x4800
	v_add_u32_e32 v185, s7, v185
	v_add_u32_e32 v183, s7, v183
	s_add_i32 s1, s1, 1
	s_add_i32 s6, s6, 64
	s_waitcnt vmcnt(0) lgkmcnt(0)
	s_barrier
	v_mfma_f32_32x32x16_bf16 v[50:65], v[102:105], v[74:77], v[50:65]
	v_mfma_f32_32x32x16_bf16 v[18:33], v[102:105], v[106:109], v[18:33]
	v_mfma_f32_32x32x16_bf16 v[34:49], v[110:113], v[74:77], v[34:49]
	v_mfma_f32_32x32x16_bf16 v[2:17], v[110:113], v[106:109], v[2:17]
	v_mfma_f32_16x16x32_bf16 v[240:243], v[244:247], v[74:77], v[240:243]
	v_mfma_f32_16x16x32_bf16 v[236:239], v[244:247], v[106:109], v[236:239]
	s_cmp_lg_u32 s21, s1
	s_cbranch_scc1 .Lgqa_top
	s_setprio 0
	s_nop 7
	v_mbcnt_lo_u32_b32 v254, -1, 0
	v_mbcnt_hi_u32_b32 v254, -1, v254
	v_and_b32_e32 v255, 15, v254
	v_lshlrev_b32_e32 v255, 2, v255
	ds_bpermute_b32 v203, v255, v240
	ds_bpermute_b32 v253, v255, v241
	s_waitcnt lgkmcnt(0)
	v_cmp_gt_u32_e32 vcc, 16, v254
	s_nop 1
	v_cndmask_b32_e32 v187, v253, v203, vcc
	v_cmp_gt_u32_e32 vcc, 32, v254
	s_nop 1
	v_cndmask_b32_e32 v187, 0, v187, vcc
	ds_bpermute_b32 v203, v255, v236
	ds_bpermute_b32 v253, v255, v237
	s_waitcnt lgkmcnt(0)
	v_cmp_gt_u32_e32 vcc, 16, v254
	s_nop 1
	v_cndmask_b32_e32 v181, v253, v203, vcc
	v_cmp_gt_u32_e32 vcc, 32, v254
	s_nop 1
	v_cndmask_b32_e32 v181, 0, v181, vcc
